# LayerNorm / GLA-finalize wave reductions: six ds_bpermute round trips replaced by DPP row reduction + row_bcast + one readlane
# speedup vs baseline: 1.0091x; 1.0058x over previous
.LBB0_294:
	v_pk_add_f32 v[148:149], v[106:107], v[122:123]
	v_pk_add_f32 v[150:151], v[108:109], v[110:111]
	v_add_f32_e32 v119, v114, v115
	v_pk_add_f32 v[148:149], v[148:149], v[150:151]
	v_add_f32_e32 v143, v120, v121
	v_add_f32_e32 v32, 0, v149
	v_add_f32_e32 v129, v148, v32
	v_pk_add_f32 v[148:149], v[116:117], v[112:113]
	v_pk_add_f32 v[150:151], v[118:119], v[142:143]
	v_pk_add_f32 v[148:149], v[148:149], v[148:149] op_sel_hi:[0,1]
	v_mov_b32_e32 v127, v149
	v_pk_add_f32 v[148:149], v[126:127], v[128:129]
	v_add_f32_e32 v135, v132, v133
	v_pk_add_f32 v[148:149], v[150:151], v[148:149]
	v_pk_add_f32 v[150:151], v[130:131], v[124:125]
	v_pk_add_f32 v[148:149], v[148:149], v[148:149] op_sel_hi:[0,1]
	v_pk_add_f32 v[150:151], v[150:151], v[150:151] op_sel_hi:[0,1]
	v_add_f32_e32 v145, v136, v137
	v_mov_b32_e32 v139, v151
	v_mov_b32_e32 v141, v149
	v_pk_add_f32 v[158:159], v[134:135], v[144:145]
	v_pk_add_f32 v[148:149], v[138:139], v[140:141]
	s_nop 0
	v_pk_add_f32 v[148:149], v[158:159], v[148:149]
	s_nop 0
	v_add_f32_e32 v32, v148, v149
	s_nop 1
	v_add_f32_dpp v32, v32, v32 quad_perm:[1,0,3,2] row_mask:0xf bank_mask:0xf
	s_nop 1
	v_add_f32_dpp v32, v32, v32 quad_perm:[2,3,0,1] row_mask:0xf bank_mask:0xf
	s_nop 1
	v_add_f32_dpp v32, v32, v32 row_half_mirror row_mask:0xf bank_mask:0xf
	s_nop 1
	v_add_f32_dpp v32, v32, v32 row_mirror row_mask:0xf bank_mask:0xf
	s_nop 1
	v_add_f32_dpp v32, v32, v32 row_bcast:15 row_mask:0xa bank_mask:0xf
	s_nop 1
	v_add_f32_dpp v32, v32, v32 row_bcast:31 row_mask:0xc bank_mask:0xf
	s_nop 1
	v_readlane_b32 vcc_lo, v32, 63
	s_waitcnt lgkmcnt(0)
	s_nop 1
	v_mov_b32_e32 v119, vcc_lo
	v_fmac_f32_e32 v111, 0xba000000, v119
	v_fmac_f32_e32 v123, 0xba000000, v119
	v_fmac_f32_e32 v109, 0xba000000, v119
	v_fmac_f32_e32 v107, 0xba000000, v119
	v_mul_f32_e32 v32, v123, v123
	v_mul_f32_e32 v127, v111, v111
	v_fmac_f32_e32 v110, 0xba000000, v119
	v_fmac_f32_e32 v122, 0xba000000, v119
	v_fmac_f32_e32 v32, v107, v107
	v_fmac_f32_e32 v127, v109, v109
	v_fmac_f32_e32 v108, 0xba000000, v119
	v_fmac_f32_e32 v106, 0xba000000, v119
	v_mul_f32_e32 v129, v122, v122
	v_add_f32_e32 v32, v32, v127
	v_mul_f32_e32 v127, v110, v110
	v_fmac_f32_e32 v129, v106, v106
	v_fmac_f32_e32 v127, v108, v108
	v_add_f32_e32 v127, v129, v127
	v_fmac_f32_e32 v113, 0xba000000, v119
	v_fmac_f32_e32 v116, 0xba000000, v119
	v_add_f32_e32 v32, v32, v127
	v_fmac_f32_e32 v117, 0xba000000, v119
	v_fmac_f32_e32 v112, 0xba000000, v119
	v_mul_f32_e32 v127, v116, v116
	v_mul_f32_e32 v129, v113, v113
	v_fmac_f32_e32 v127, v112, v112
	v_fmac_f32_e32 v129, v117, v117
	v_add_f32_e32 v127, v127, v129
	v_fmac_f32_e32 v121, 0xba000000, v119
	v_fmac_f32_e32 v115, 0xba000000, v119
	v_add_f32_e32 v32, v127, v32
	v_fmac_f32_e32 v120, 0xba000000, v119
	v_fmac_f32_e32 v114, 0xba000000, v119
	v_mul_f32_e32 v127, v115, v115
	v_mul_f32_e32 v129, v121, v121
	v_fmac_f32_e32 v127, v114, v114
	v_fmac_f32_e32 v129, v120, v120
	v_add_f32_e32 v127, v127, v129
	v_fmac_f32_e32 v128, 0xba000000, v119
	v_fmac_f32_e32 v142, 0xba000000, v119
	v_add_f32_e32 v32, v127, v32
	v_fmac_f32_e32 v126, 0xba000000, v119
	v_fmac_f32_e32 v118, 0xba000000, v119
	v_mul_f32_e32 v127, v142, v142
	v_mul_f32_e32 v129, v128, v128
	v_fmac_f32_e32 v127, v118, v118
	v_fmac_f32_e32 v129, v126, v126
	v_add_f32_e32 v127, v127, v129
	v_fmac_f32_e32 v125, 0xba000000, v119
	v_fmac_f32_e32 v130, 0xba000000, v119
	v_add_f32_e32 v32, v127, v32
	v_fmac_f32_e32 v131, 0xba000000, v119
	v_fmac_f32_e32 v124, 0xba000000, v119
	v_mul_f32_e32 v127, v130, v130
	v_mul_f32_e32 v129, v125, v125
	v_fmac_f32_e32 v127, v124, v124
	v_fmac_f32_e32 v129, v131, v131
	v_add_f32_e32 v127, v127, v129
	v_fmac_f32_e32 v137, 0xba000000, v119
	v_fmac_f32_e32 v133, 0xba000000, v119
	v_add_f32_e32 v32, v127, v32
	v_fmac_f32_e32 v136, 0xba000000, v119
	v_fmac_f32_e32 v132, 0xba000000, v119
	v_mul_f32_e32 v127, v133, v133
	v_mul_f32_e32 v129, v137, v137
	v_fmac_f32_e32 v127, v132, v132
	v_fmac_f32_e32 v129, v136, v136
	v_add_f32_e32 v127, v127, v129
	v_fmac_f32_e32 v140, 0xba000000, v119
	v_fmac_f32_e32 v144, 0xba000000, v119
	v_add_f32_e32 v32, v127, v32
	v_fmac_f32_e32 v138, 0xba000000, v119
	v_fmac_f32_e32 v134, 0xba000000, v119
	v_mul_f32_e32 v127, v144, v144
	v_mul_f32_e32 v129, v140, v140
	v_fmac_f32_e32 v127, v134, v134
	v_fmac_f32_e32 v129, v138, v138
	v_add_f32_e32 v127, v127, v129
	v_add_f32_e32 v32, v127, v32
	s_nop 1
	v_add_f32_dpp v32, v32, v32 quad_perm:[1,0,3,2] row_mask:0xf bank_mask:0xf
	s_nop 1
	v_add_f32_dpp v32, v32, v32 quad_perm:[2,3,0,1] row_mask:0xf bank_mask:0xf
	s_nop 1
	v_add_f32_dpp v32, v32, v32 row_half_mirror row_mask:0xf bank_mask:0xf
	s_nop 1
	v_add_f32_dpp v32, v32, v32 row_mirror row_mask:0xf bank_mask:0xf
	s_nop 1
	v_add_f32_dpp v32, v32, v32 row_bcast:15 row_mask:0xa bank_mask:0xf
	s_nop 1
	v_add_f32_dpp v32, v32, v32 row_bcast:31 row_mask:0xc bank_mask:0xf
	s_nop 1
	v_readlane_b32 vcc_lo, v32, 63
	s_waitcnt lgkmcnt(0)
	s_nop 1
	v_mov_b32_e32 v32, vcc_lo
	v_fmamk_f32 v32, v32, 0x3a000000, v218
	v_mul_f32_e32 v127, 0x4f800000, v32
	v_cmp_gt_f32_e32 vcc, s30, v32
	s_nop 1
	v_cndmask_b32_e32 v32, v32, v127, vcc
	v_sqrt_f32_e32 v127, v32
	s_nop 0
	v_add_u32_e32 v129, -1, v127
	v_fma_f32 v135, -v129, v127, v32
	v_cmp_ge_f32_e64 s[4:5], 0, v135
	v_add_u32_e32 v135, 1, v127
	s_nop 0
	v_cndmask_b32_e64 v129, v127, v129, s[4:5]
	v_fma_f32 v127, -v135, v127, v32
	v_cmp_lt_f32_e64 s[4:5], 0, v127
	s_nop 1
	v_cndmask_b32_e64 v127, v129, v135, s[4:5]
	v_mul_f32_e32 v129, 0x37800000, v127
	v_cndmask_b32_e32 v127, v127, v129, vcc
	v_cmp_class_f32_e32 vcc, v32, v219
	s_nop 1
	v_cndmask_b32_e32 v32, v127, v32, vcc
	v_div_scale_f32 v127, s[4:5], v32, v32, 1.0
	v_rcp_f32_e32 v129, v127
	s_nop 0
	v_fma_f32 v135, -v127, v129, 1.0
	v_fmac_f32_e32 v129, v135, v129
	v_div_scale_f32 v135, vcc, 1.0, v32, 1.0
	v_mul_f32_e32 v139, v135, v129
	v_fma_f32 v141, -v127, v139, v135
	v_fmac_f32_e32 v139, v141, v129
	v_fma_f32 v127, -v127, v139, v135
	v_div_fmas_f32 v127, v127, v129, v139
	v_div_fixup_f32 v32, v127, v32, 1.0
	s_and_saveexec_b64 s[4:5], s[12:13]
	s_cbranch_execz .LBB0_291
	v_mul_f32_e32 v148, 0x3a000000, v119
	v_mov_b32_e32 v149, v32
	v_mov_b64_e32 v[150:151], s[70:71]
	flat_store_dwordx2 v[150:151], v[148:149]
	s_branch .LBB0_291

.LBB0_321:
	v_pk_add_f32 v[158:159], v[114:115], v[116:117]
	v_pk_add_f32 v[160:161], v[104:105], v[106:107]
	v_add_f32_e32 v131, v110, v111
	v_pk_add_f32 v[158:159], v[158:159], v[160:161]
	v_add_f32_e32 v135, v112, v113
	v_add_f32_e32 v127, 0, v159
	v_add_f32_e32 v133, v158, v127
	v_pk_add_f32 v[158:159], v[150:151], v[108:109]
	v_pk_add_f32 v[160:161], v[130:131], v[134:135]
	v_pk_add_f32 v[158:159], v[158:159], v[158:159] op_sel_hi:[0,1]
	v_mov_b32_e32 v127, v159
	v_pk_add_f32 v[158:159], v[126:127], v[132:133]
	v_add_f32_e32 v141, v136, v137
	v_pk_add_f32 v[158:159], v[160:161], v[158:159]
	v_pk_add_f32 v[160:161], v[148:149], v[128:129]
	v_pk_add_f32 v[158:159], v[158:159], v[158:159] op_sel_hi:[0,1]
	v_pk_add_f32 v[160:161], v[160:161], v[160:161] op_sel_hi:[0,1]
	v_add_f32_e32 v145, v138, v139
	v_mov_b32_e32 v143, v161
	v_mov_b32_e32 v147, v159
	v_pk_add_f32 v[162:163], v[140:141], v[144:145]
	v_pk_add_f32 v[158:159], v[142:143], v[146:147]
	s_nop 0
	v_pk_add_f32 v[158:159], v[162:163], v[158:159]
	s_nop 0
	v_add_f32_e32 v127, v158, v159
	s_nop 1
	v_add_f32_dpp v127, v127, v127 quad_perm:[1,0,3,2] row_mask:0xf bank_mask:0xf
	s_nop 1
	v_add_f32_dpp v127, v127, v127 quad_perm:[2,3,0,1] row_mask:0xf bank_mask:0xf
	s_nop 1
	v_add_f32_dpp v127, v127, v127 row_half_mirror row_mask:0xf bank_mask:0xf
	s_nop 1
	v_add_f32_dpp v127, v127, v127 row_mirror row_mask:0xf bank_mask:0xf
	s_nop 1
	v_add_f32_dpp v127, v127, v127 row_bcast:15 row_mask:0xa bank_mask:0xf
	s_nop 1
	v_add_f32_dpp v127, v127, v127 row_bcast:31 row_mask:0xc bank_mask:0xf
	s_nop 1
	v_readlane_b32 vcc_lo, v127, 63
	s_waitcnt lgkmcnt(0)
	s_nop 1
	v_mov_b32_e32 v127, vcc_lo
	v_fmac_f32_e32 v117, 0xba000000, v127
	v_fmac_f32_e32 v116, 0xba000000, v127
	v_fmac_f32_e32 v107, 0xba000000, v127
	v_fmac_f32_e32 v115, 0xba000000, v127
	v_fmac_f32_e32 v106, 0xba000000, v127
	v_fmac_f32_e32 v114, 0xba000000, v127
	v_mov_b32_e32 v160, v117
	v_mov_b32_e32 v161, v116
	v_fmac_f32_e32 v105, 0xba000000, v127
	v_fmac_f32_e32 v104, 0xba000000, v127
	v_mov_b32_e32 v158, v115
	v_mov_b32_e32 v159, v114
	v_pk_mul_f32 v[160:161], v[160:161], v[160:161]
	v_mov_b32_e32 v162, v107
	v_mov_b32_e32 v163, v106
	v_pk_fma_f32 v[158:159], v[158:159], v[158:159], v[160:161]
	v_mov_b32_e32 v160, v105
	v_mov_b32_e32 v161, v104
	v_pk_mul_f32 v[162:163], v[162:163], v[162:163]
	v_fmac_f32_e32 v150, 0xba000000, v127
	v_pk_fma_f32 v[160:161], v[160:161], v[160:161], v[162:163]
	v_fmac_f32_e32 v109, 0xba000000, v127
	v_fmac_f32_e32 v151, 0xba000000, v127
	v_pk_add_f32 v[158:159], v[158:159], v[160:161]
	v_fmac_f32_e32 v108, 0xba000000, v127
	v_mov_b32_e32 v160, v151
	v_mov_b32_e32 v161, v109
	v_mov_b32_e32 v109, v150
	v_pk_mul_f32 v[150:151], v[160:161], v[160:161]
	v_pk_mul_f32 v[162:163], v[108:109], v[108:109]
	v_fmac_f32_e32 v110, 0xba000000, v127
	v_pk_mov_b32 v[164:165], v[162:163], v[150:151] op_sel:[1,0]
	v_mov_b32_e32 v163, v151
	v_pk_add_f32 v[150:151], v[164:165], v[162:163]
	v_fmac_f32_e32 v111, 0xba000000, v127
	v_mul_f32_e32 v162, v110, v110
	v_fmac_f32_e32 v112, 0xba000000, v127
	v_pk_fma_f32 v[162:163], v[110:111], v[110:111], v[162:163] op_sel_hi:[1,1,0]
	v_fmac_f32_e32 v113, 0xba000000, v127
	v_mul_f32_e32 v162, v112, v112
	v_pk_fma_f32 v[164:165], v[112:113], v[112:113], v[162:163] op_sel_hi:[1,1,0]
	v_fmac_f32_e32 v134, 0xba000000, v127
	v_fmac_f32_e32 v130, 0xba000000, v127
	v_pk_add_f32 v[158:159], v[158:159], v[158:159] op_sel_hi:[0,1]
	v_pk_add_f32 v[150:151], v[150:151], v[150:151] op_sel_hi:[0,1]
	v_fmac_f32_e32 v132, 0xba000000, v127
	v_fmac_f32_e32 v126, 0xba000000, v127
	v_mul_f32_e32 v162, v130, v130
	v_mul_f32_e32 v164, v134, v134
	v_mul_f32_e32 v150, v126, v126
	v_mul_f32_e32 v158, v132, v132
	v_fmac_f32_e32 v148, 0xba000000, v127
	v_fmac_f32_e32 v129, 0xba000000, v127
	v_fmac_f32_e32 v149, 0xba000000, v127
	v_pk_add_f32 v[162:163], v[162:163], v[164:165]
	v_pk_add_f32 v[150:151], v[150:151], v[158:159]
	v_fmac_f32_e32 v128, 0xba000000, v127
	v_mov_b32_e32 v158, v149
	v_mov_b32_e32 v159, v129
	v_mov_b32_e32 v129, v148
	v_pk_add_f32 v[150:151], v[162:163], v[150:151]
	v_pk_mul_f32 v[148:149], v[158:159], v[158:159]
	v_pk_mul_f32 v[162:163], v[128:129], v[128:129]
	v_fmac_f32_e32 v136, 0xba000000, v127
	v_pk_mov_b32 v[164:165], v[162:163], v[148:149] op_sel:[1,0]
	v_mov_b32_e32 v163, v149
	v_pk_add_f32 v[148:149], v[164:165], v[162:163]
	v_fmac_f32_e32 v137, 0xba000000, v127
	v_mul_f32_e32 v162, v136, v136
	v_fmac_f32_e32 v138, 0xba000000, v127
	v_pk_fma_f32 v[162:163], v[136:137], v[136:137], v[162:163] op_sel_hi:[1,1,0]
	v_fmac_f32_e32 v139, 0xba000000, v127
	v_mul_f32_e32 v162, v138, v138
	v_pk_fma_f32 v[164:165], v[138:139], v[138:139], v[162:163] op_sel_hi:[1,1,0]
	v_fmac_f32_e32 v144, 0xba000000, v127
	v_fmac_f32_e32 v140, 0xba000000, v127
	v_fmac_f32_e32 v146, 0xba000000, v127
	v_fmac_f32_e32 v142, 0xba000000, v127
	v_pk_add_f32 v[150:151], v[150:151], v[150:151] op_sel_hi:[0,1]
	v_pk_add_f32 v[148:149], v[148:149], v[148:149] op_sel_hi:[0,1]
	v_mul_f32_e32 v162, v140, v140
	v_mul_f32_e32 v164, v144, v144
	v_mul_f32_e32 v148, v142, v142
	v_mul_f32_e32 v150, v146, v146
	v_pk_add_f32 v[162:163], v[162:163], v[164:165]
	v_pk_add_f32 v[148:149], v[148:149], v[150:151]
	v_mov_b32_e32 v141, v144
	v_pk_add_f32 v[148:149], v[162:163], v[148:149]
	v_mov_b32_e32 v143, v146
	v_add_f32_e32 v127, v148, v149
	v_mov_b32_e32 v148, v114
	v_mov_b32_e32 v149, v116
	v_mov_b32_e32 v144, v95
	v_mov_b32_e32 v146, v97
	s_nop 1
	v_add_f32_dpp v127, v127, v127 quad_perm:[1,0,3,2] row_mask:0xf bank_mask:0xf
	s_nop 1
	v_add_f32_dpp v127, v127, v127 quad_perm:[2,3,0,1] row_mask:0xf bank_mask:0xf
	s_nop 1
	v_add_f32_dpp v127, v127, v127 row_half_mirror row_mask:0xf bank_mask:0xf
	s_nop 1
	v_add_f32_dpp v127, v127, v127 row_mirror row_mask:0xf bank_mask:0xf
	s_nop 1
	v_add_f32_dpp v127, v127, v127 row_bcast:15 row_mask:0xa bank_mask:0xf
	s_nop 1
	v_add_f32_dpp v127, v127, v127 row_bcast:31 row_mask:0xc bank_mask:0xf
	s_nop 1
	v_readlane_b32 vcc_lo, v127, 63
	s_waitcnt lgkmcnt(0)
	s_nop 1
	v_mov_b32_e32 v114, vcc_lo
	v_fmamk_f32 v114, v114, 0x3a000000, v218
	v_mul_f32_e32 v116, 0x4f800000, v114
	v_cmp_gt_f32_e32 vcc, s30, v114
	s_nop 1
	v_cndmask_b32_e32 v127, v114, v116, vcc
	v_sqrt_f32_e32 v131, v127
	v_mov_b32_e32 v114, v104
	v_mov_b32_e32 v116, v115
	v_add_u32_e32 v104, -1, v131
	v_fma_f32 v115, -v104, v131, v127
	v_cmp_ge_f32_e64 s[4:5], 0, v115
	v_add_u32_e32 v115, 1, v131
	s_nop 0
	v_cndmask_b32_e64 v104, v131, v104, s[4:5]
	v_fma_f32 v131, -v115, v131, v127
	v_cmp_lt_f32_e64 s[4:5], 0, v131
	s_nop 1
	v_cndmask_b32_e64 v104, v104, v115, s[4:5]
	v_mul_f32_e32 v115, 0x37800000, v104
	v_cndmask_b32_e32 v104, v104, v115, vcc
	v_cmp_class_f32_e32 vcc, v127, v219
	v_mov_b32_e32 v115, v106
	v_mov_b32_e32 v106, v105
	v_cndmask_b32_e32 v104, v104, v127, vcc
	v_div_scale_f32 v127, s[4:5], v104, v104, 1.0
	v_rcp_f32_e32 v131, v127
	s_lshl_b64 s[4:5], s[38:39], 2
	s_add_u32 s4, s6, s4
	s_addc_u32 s5, s7, s5
	v_fma_f32 v105, -v127, v131, 1.0
	v_fmac_f32_e32 v131, v105, v131
	v_div_scale_f32 v105, vcc, 1.0, v104, 1.0
	v_mul_f32_e32 v133, v105, v131
	v_fma_f32 v135, -v127, v133, v105
	v_fmac_f32_e32 v133, v135, v131
	v_fma_f32 v105, -v127, v133, v105
	v_div_fmas_f32 v105, v105, v131, v133
	v_div_fixup_f32 v104, v105, v104, 1.0
	v_pk_mul_f32 v[116:117], v[116:117], v[104:105] op_sel_hi:[1,0]
	v_pk_mul_f32 v[106:107], v[106:107], v[104:105] op_sel_hi:[1,0]
	v_pk_mul_f32 v[148:149], v[148:149], v[104:105] op_sel_hi:[1,0]
	v_pk_mul_f32 v[114:115], v[114:115], v[104:105] op_sel_hi:[1,0]
	v_mov_b32_e32 v131, v134
	v_mov_b32_e32 v127, v132
	v_pk_mul_f32 v[150:151], v[108:109], v[104:105] op_sel_hi:[1,0]
	v_pk_mul_f32 v[160:161], v[160:161], v[104:105] op_sel_hi:[1,0]
	v_pk_mul_f32 v[162:163], v[110:111], v[104:105] op_sel_hi:[1,0]
	v_pk_mul_f32 v[112:113], v[112:113], v[104:105] op_sel_hi:[1,0]
	v_pk_mul_f32 v[130:131], v[130:131], v[104:105] op_sel_hi:[1,0]
	v_pk_mul_f32 v[126:127], v[126:127], v[104:105] op_sel_hi:[1,0]
	v_pk_mul_f32 v[128:129], v[128:129], v[104:105] op_sel_hi:[1,0]
	v_pk_mul_f32 v[132:133], v[158:159], v[104:105] op_sel_hi:[1,0]
	v_pk_mul_f32 v[134:135], v[136:137], v[104:105] op_sel_hi:[1,0]
	v_pk_mul_f32 v[136:137], v[138:139], v[104:105] op_sel_hi:[1,0]
	v_pk_mul_f32 v[138:139], v[140:141], v[104:105] op_sel_hi:[1,0]
	v_pk_mul_f32 v[140:141], v[142:143], v[104:105] op_sel_hi:[1,0]
	v_pk_fma_f32 v[106:107], v[16:17], v[106:107], v[12:13]
	v_pk_fma_f32 v[104:105], v[14:15], v[116:117], v[10:11]
	v_pk_fma_f32 v[110:111], v[4:5], v[114:115], v[8:9]
	v_pk_fma_f32 v[108:109], v[2:3], v[148:149], v[6:7]
	v_lshl_add_u64 v[114:115], v[98:99], 2, s[4:5]
	s_add_u32 s72, s72, 0x800
	global_store_dwordx4 v[114:115], v[104:107], off
	global_store_dwordx4 v[114:115], v[108:111], off offset:16
	s_addc_u32 s73, s73, 0
	v_pk_fma_f32 v[106:107], v[32:33], v[160:161], v[28:29]
	v_pk_fma_f32 v[104:105], v[30:31], v[150:151], v[26:27]
	v_pk_fma_f32 v[110:111], v[20:21], v[112:113], v[24:25]
	v_pk_fma_f32 v[108:109], v[18:19], v[162:163], v[22:23]
	global_store_dwordx4 v[114:115], v[104:107], off offset:2048
	global_store_dwordx4 v[114:115], v[108:111], off offset:2064
	v_lshl_add_u64 v[112:113], v[102:103], 2, s[4:5]
	v_pk_fma_f32 v[106:107], v[36:37], v[126:127], v[40:41]
	v_pk_fma_f32 v[104:105], v[34:35], v[130:131], v[38:39]
	v_pk_fma_f32 v[110:111], v[44:45], v[132:133], v[48:49]
	v_pk_fma_f32 v[108:109], v[42:43], v[128:129], v[46:47]
	s_add_u32 s70, s70, 0x1000
	global_store_dwordx4 v[112:113], v[104:107], off
	global_store_dwordx4 v[112:113], v[108:111], off offset:16
	v_lshl_add_u64 v[112:113], v[100:101], 2, s[4:5]
	v_pk_fma_f32 v[106:107], v[64:65], v[136:137], v[60:61]
	v_pk_fma_f32 v[104:105], v[62:63], v[134:135], v[58:59]
	v_pk_fma_f32 v[110:111], v[52:53], v[140:141], v[56:57]
	v_pk_fma_f32 v[108:109], v[50:51], v[138:139], v[54:55]
	s_addc_u32 s71, s71, 0
	global_store_dwordx4 v[112:113], v[104:107], off
	global_store_dwordx4 v[112:113], v[108:111], off offset:16
	s_cmpk_eq_u32 s70, 0x8000
	v_mov_b32_e32 v115, v76
	v_mov_b32_e32 v117, v67
	v_mov_b32_e32 v105, v80
	v_mov_b32_e32 v107, v77
	v_mov_b32_e32 v114, v74
	v_mov_b32_e32 v116, v69
	v_mov_b32_e32 v104, v82
	v_mov_b32_e32 v106, v81
	v_mov_b32_e32 v108, v72
	v_mov_b32_e32 v150, v71
	v_mov_b32_e32 v151, v84
	v_mov_b32_e32 v109, v85
	v_mov_b32_e32 v110, v70
	v_mov_b32_e32 v111, v73
	v_mov_b32_e32 v112, v86
	v_mov_b32_e32 v113, v87
	v_mov_b32_e32 v130, v68
	v_mov_b32_e32 v134, v75
	v_mov_b32_e32 v126, v88
	v_mov_b32_e32 v132, v89
	v_mov_b32_e32 v128, v66
	v_mov_b32_e32 v148, v79
	v_mov_b32_e32 v149, v90
	v_mov_b32_e32 v129, v91
	v_mov_b32_e32 v136, v0
	v_mov_b32_e32 v137, v83
	v_mov_b32_e32 v138, v92
	v_mov_b32_e32 v139, v93
	v_mov_b32_e32 v140, v78
	v_mov_b32_e32 v142, v94
	s_cbranch_scc1 .LBB0_324

.LBB0_346:
	v_pk_add_f32 v[148:149], v[106:107], v[122:123]
	v_pk_add_f32 v[150:151], v[108:109], v[110:111]
	v_add_f32_e32 v119, v114, v115
	v_pk_add_f32 v[148:149], v[148:149], v[150:151]
	v_add_f32_e32 v143, v120, v121
	v_add_f32_e32 v32, 0, v149
	v_add_f32_e32 v129, v148, v32
	v_pk_add_f32 v[148:149], v[116:117], v[112:113]
	v_pk_add_f32 v[150:151], v[118:119], v[142:143]
	v_pk_add_f32 v[148:149], v[148:149], v[148:149] op_sel_hi:[0,1]
	v_mov_b32_e32 v127, v149
	v_pk_add_f32 v[148:149], v[126:127], v[128:129]
	v_add_f32_e32 v135, v132, v133
	v_pk_add_f32 v[148:149], v[150:151], v[148:149]
	v_pk_add_f32 v[150:151], v[130:131], v[124:125]
	v_pk_add_f32 v[148:149], v[148:149], v[148:149] op_sel_hi:[0,1]
	v_pk_add_f32 v[150:151], v[150:151], v[150:151] op_sel_hi:[0,1]
	v_add_f32_e32 v145, v136, v137
	v_mov_b32_e32 v139, v151
	v_mov_b32_e32 v141, v149
	v_pk_add_f32 v[158:159], v[134:135], v[144:145]
	v_pk_add_f32 v[148:149], v[138:139], v[140:141]
	s_nop 0
	v_pk_add_f32 v[148:149], v[158:159], v[148:149]
	s_nop 0
	v_add_f32_e32 v32, v148, v149
	s_nop 1
	v_add_f32_dpp v32, v32, v32 quad_perm:[1,0,3,2] row_mask:0xf bank_mask:0xf
	s_nop 1
	v_add_f32_dpp v32, v32, v32 quad_perm:[2,3,0,1] row_mask:0xf bank_mask:0xf
	s_nop 1
	v_add_f32_dpp v32, v32, v32 row_half_mirror row_mask:0xf bank_mask:0xf
	s_nop 1
	v_add_f32_dpp v32, v32, v32 row_mirror row_mask:0xf bank_mask:0xf
	s_nop 1
	v_add_f32_dpp v32, v32, v32 row_bcast:15 row_mask:0xa bank_mask:0xf
	s_nop 1
	v_add_f32_dpp v32, v32, v32 row_bcast:31 row_mask:0xc bank_mask:0xf
	s_nop 1
	v_readlane_b32 vcc_lo, v32, 63
	s_waitcnt lgkmcnt(0)
	s_nop 1
	v_mov_b32_e32 v119, vcc_lo
	v_fmac_f32_e32 v111, 0xba000000, v119
	v_fmac_f32_e32 v123, 0xba000000, v119
	v_fmac_f32_e32 v109, 0xba000000, v119
	v_fmac_f32_e32 v107, 0xba000000, v119
	v_mul_f32_e32 v32, v123, v123
	v_mul_f32_e32 v127, v111, v111
	v_fmac_f32_e32 v110, 0xba000000, v119
	v_fmac_f32_e32 v122, 0xba000000, v119
	v_fmac_f32_e32 v32, v107, v107
	v_fmac_f32_e32 v127, v109, v109
	v_fmac_f32_e32 v108, 0xba000000, v119
	v_fmac_f32_e32 v106, 0xba000000, v119
	v_mul_f32_e32 v129, v122, v122
	v_add_f32_e32 v32, v32, v127
	v_mul_f32_e32 v127, v110, v110
	v_fmac_f32_e32 v129, v106, v106
	v_fmac_f32_e32 v127, v108, v108
	v_add_f32_e32 v127, v129, v127
	v_fmac_f32_e32 v113, 0xba000000, v119
	v_fmac_f32_e32 v116, 0xba000000, v119
	v_add_f32_e32 v32, v32, v127
	v_fmac_f32_e32 v117, 0xba000000, v119
	v_fmac_f32_e32 v112, 0xba000000, v119
	v_mul_f32_e32 v127, v116, v116
	v_mul_f32_e32 v129, v113, v113
	v_fmac_f32_e32 v127, v112, v112
	v_fmac_f32_e32 v129, v117, v117
	v_add_f32_e32 v127, v127, v129
	v_fmac_f32_e32 v121, 0xba000000, v119
	v_fmac_f32_e32 v115, 0xba000000, v119
	v_add_f32_e32 v32, v127, v32
	v_fmac_f32_e32 v120, 0xba000000, v119
	v_fmac_f32_e32 v114, 0xba000000, v119
	v_mul_f32_e32 v127, v115, v115
	v_mul_f32_e32 v129, v121, v121
	v_fmac_f32_e32 v127, v114, v114
	v_fmac_f32_e32 v129, v120, v120
	v_add_f32_e32 v127, v127, v129
	v_fmac_f32_e32 v128, 0xba000000, v119
	v_fmac_f32_e32 v142, 0xba000000, v119
	v_add_f32_e32 v32, v127, v32
	v_fmac_f32_e32 v126, 0xba000000, v119
	v_fmac_f32_e32 v118, 0xba000000, v119
	v_mul_f32_e32 v127, v142, v142
	v_mul_f32_e32 v129, v128, v128
	v_fmac_f32_e32 v127, v118, v118
	v_fmac_f32_e32 v129, v126, v126
	v_add_f32_e32 v127, v127, v129
	v_fmac_f32_e32 v125, 0xba000000, v119
	v_fmac_f32_e32 v130, 0xba000000, v119
	v_add_f32_e32 v32, v127, v32
	v_fmac_f32_e32 v131, 0xba000000, v119
	v_fmac_f32_e32 v124, 0xba000000, v119
	v_mul_f32_e32 v127, v130, v130
	v_mul_f32_e32 v129, v125, v125
	v_fmac_f32_e32 v127, v124, v124
	v_fmac_f32_e32 v129, v131, v131
	v_add_f32_e32 v127, v127, v129
	v_fmac_f32_e32 v137, 0xba000000, v119
	v_fmac_f32_e32 v133, 0xba000000, v119
	v_add_f32_e32 v32, v127, v32
	v_fmac_f32_e32 v136, 0xba000000, v119
	v_fmac_f32_e32 v132, 0xba000000, v119
	v_mul_f32_e32 v127, v133, v133
	v_mul_f32_e32 v129, v137, v137
	v_fmac_f32_e32 v127, v132, v132
	v_fmac_f32_e32 v129, v136, v136
	v_add_f32_e32 v127, v127, v129
	v_fmac_f32_e32 v140, 0xba000000, v119
	v_fmac_f32_e32 v144, 0xba000000, v119
	v_add_f32_e32 v32, v127, v32
	v_fmac_f32_e32 v138, 0xba000000, v119
	v_fmac_f32_e32 v134, 0xba000000, v119
	v_mul_f32_e32 v127, v144, v144
	v_mul_f32_e32 v129, v140, v140
	v_fmac_f32_e32 v127, v134, v134
	v_fmac_f32_e32 v129, v138, v138
	v_add_f32_e32 v127, v127, v129
	v_add_f32_e32 v32, v127, v32
	s_nop 1
	v_add_f32_dpp v32, v32, v32 quad_perm:[1,0,3,2] row_mask:0xf bank_mask:0xf
	s_nop 1
	v_add_f32_dpp v32, v32, v32 quad_perm:[2,3,0,1] row_mask:0xf bank_mask:0xf
	s_nop 1
	v_add_f32_dpp v32, v32, v32 row_half_mirror row_mask:0xf bank_mask:0xf
	s_nop 1
	v_add_f32_dpp v32, v32, v32 row_mirror row_mask:0xf bank_mask:0xf
	s_nop 1
	v_add_f32_dpp v32, v32, v32 row_bcast:15 row_mask:0xa bank_mask:0xf
	s_nop 1
	v_add_f32_dpp v32, v32, v32 row_bcast:31 row_mask:0xc bank_mask:0xf
	s_nop 1
	v_readlane_b32 vcc_lo, v32, 63
	s_waitcnt lgkmcnt(0)
	s_nop 1
	v_mov_b32_e32 v32, vcc_lo
	v_fmamk_f32 v32, v32, 0x3a000000, v218
	v_mul_f32_e32 v127, 0x4f800000, v32
	v_cmp_gt_f32_e32 vcc, s30, v32
	s_nop 1
	v_cndmask_b32_e32 v32, v32, v127, vcc
	v_sqrt_f32_e32 v127, v32
	s_nop 0
	v_add_u32_e32 v129, -1, v127
	v_fma_f32 v135, -v129, v127, v32
	v_cmp_ge_f32_e64 s[4:5], 0, v135
	v_add_u32_e32 v135, 1, v127
	s_nop 0
	v_cndmask_b32_e64 v129, v127, v129, s[4:5]
	v_fma_f32 v127, -v135, v127, v32
	v_cmp_lt_f32_e64 s[4:5], 0, v127
	s_nop 1
	v_cndmask_b32_e64 v127, v129, v135, s[4:5]
	v_mul_f32_e32 v129, 0x37800000, v127
	v_cndmask_b32_e32 v127, v127, v129, vcc
	v_cmp_class_f32_e32 vcc, v32, v219
	s_nop 1
	v_cndmask_b32_e32 v32, v127, v32, vcc
	v_div_scale_f32 v127, s[4:5], v32, v32, 1.0
	v_rcp_f32_e32 v129, v127
	s_nop 0
	v_fma_f32 v135, -v127, v129, 1.0
	v_fmac_f32_e32 v129, v135, v129
	v_div_scale_f32 v135, vcc, 1.0, v32, 1.0
	v_mul_f32_e32 v139, v135, v129
	v_fma_f32 v141, -v127, v139, v135
	v_fmac_f32_e32 v139, v141, v129
	v_fma_f32 v127, -v127, v139, v135
	v_div_fmas_f32 v127, v127, v129, v139
	v_div_fixup_f32 v32, v127, v32, 1.0
	s_and_saveexec_b64 s[4:5], s[10:11]
	s_cbranch_execz .LBB0_343
	v_mul_f32_e32 v148, 0x3a000000, v119
	v_mov_b32_e32 v149, v32
	v_mov_b64_e32 v[150:151], s[18:19]
	flat_store_dwordx2 v[150:151], v[148:149]
	s_branch .LBB0_343

.LBB0_471:
	v_lshl_add_u64 v[12:13], s[56:57], 0, v[10:11]
	v_add_co_u32_e32 v18, vcc, 0x17f01000, v12
	v_add_u32_e32 v35, s40, v30
	s_nop 0
	v_addc_co_u32_e32 v19, vcc, 0, v13, vcc
	flat_load_dwordx2 v[18:19], v[18:19] offset:512
	ds_read2_b64 v[14:17], v35 offset1:1
	s_addk_i32 s40, 0x808
	s_cmpk_eq_i32 s40, 0x2020
	s_waitcnt lgkmcnt(0)
	v_mov_b32_e32 v38, v15
	v_mov_b32_e32 v39, v17
	v_mov_b32_e32 v36, v14
	v_mov_b32_e32 v37, v16
	v_pk_mul_f32 v[38:39], v[38:39], v[38:39]
	s_nop 0
	v_pk_fma_f32 v[36:37], v[36:37], v[36:37], v[38:39]
	s_nop 0
	v_add_f32_e32 v36, v36, v37
	s_nop 1
	v_add_f32_dpp v36, v36, v36 quad_perm:[1,0,3,2] row_mask:0xf bank_mask:0xf
	s_nop 1
	v_add_f32_dpp v36, v36, v36 quad_perm:[2,3,0,1] row_mask:0xf bank_mask:0xf
	s_nop 1
	v_add_f32_dpp v36, v36, v36 row_half_mirror row_mask:0xf bank_mask:0xf
	s_nop 1
	v_add_f32_dpp v36, v36, v36 row_mirror row_mask:0xf bank_mask:0xf
	s_nop 1
	v_add_f32_dpp v36, v36, v36 row_bcast:15 row_mask:0xa bank_mask:0xf
	s_nop 1
	v_add_f32_dpp v36, v36, v36 row_bcast:31 row_mask:0xc bank_mask:0xf
	s_nop 1
	v_readlane_b32 vcc_lo, v36, 63
	s_waitcnt lgkmcnt(0)
	s_nop 1
	v_mov_b32_e32 v36, vcc_lo
	v_fmamk_f32 v36, v36, 0x3b800000, v218
	v_cmp_gt_f32_e32 vcc, s30, v36
	v_mul_f32_e32 v37, 0x4f800000, v36
	s_nop 0
	v_cndmask_b32_e32 v36, v36, v37, vcc
	v_sqrt_f32_e32 v37, v36
	s_nop 0
	v_add_u32_e32 v38, -1, v37
	v_fma_f32 v39, -v38, v37, v36
	v_cmp_ge_f32_e64 s[0:1], 0, v39
	v_add_u32_e32 v39, 1, v37
	s_nop 0
	v_cndmask_b32_e64 v38, v37, v38, s[0:1]
	v_fma_f32 v37, -v39, v37, v36
	v_cmp_lt_f32_e64 s[0:1], 0, v37
	s_nop 1
	v_cndmask_b32_e64 v37, v38, v39, s[0:1]
	v_mul_f32_e32 v38, 0x37800000, v37
	v_cndmask_b32_e32 v37, v37, v38, vcc
	v_cmp_class_f32_e32 vcc, v36, v219
	s_nop 1
	v_cndmask_b32_e32 v36, v37, v36, vcc
	v_div_scale_f32 v37, s[0:1], v36, v36, 1.0
	v_rcp_f32_e32 v38, v37
	s_mov_b32 s0, 0x17f02000
	v_fma_f32 v39, -v37, v38, 1.0
	v_fmac_f32_e32 v38, v39, v38
	v_div_scale_f32 v39, vcc, 1.0, v36, 1.0
	v_mul_f32_e32 v40, v39, v38
	v_fma_f32 v41, -v37, v40, v39
	v_fmac_f32_e32 v40, v41, v38
	v_fma_f32 v37, -v37, v40, v39
	v_div_fmas_f32 v37, v37, v38, v40
	s_waitcnt vmcnt(0)
	v_lshlrev_b32_e32 v38, 16, v18
	v_and_b32_e32 v39, 0xffff0000, v18
	v_mul_f32_e32 v18, 0xbfb8aa3b, v38
	v_exp_f32_e32 v18, v18
	v_div_fixup_f32 v36, v37, v36, 1.0
	v_add_f32_e32 v18, 1.0, v18
	v_rcp_f32_e32 v40, v18
	v_mul_f32_e32 v18, 0xbfb8aa3b, v39
	v_exp_f32_e32 v18, v18
	s_nop 0
	v_add_f32_e32 v18, 1.0, v18
	v_rcp_f32_e32 v41, v18
	v_lshlrev_b32_e32 v18, 16, v19
	v_mul_f32_e32 v37, 0xbfb8aa3b, v18
	v_exp_f32_e32 v37, v37
	v_and_b32_e32 v19, 0xffff0000, v19
	v_pk_mul_f32 v[38:39], v[40:41], v[38:39]
	v_add_f32_e32 v37, 1.0, v37
	v_rcp_f32_e32 v42, v37
	v_mul_f32_e32 v37, 0xbfb8aa3b, v19
	v_exp_f32_e32 v37, v37
	s_nop 0
	v_add_f32_e32 v37, 1.0, v37
	v_rcp_f32_e32 v43, v37
	v_pk_mul_f32 v[16:17], v[16:17], v[36:37] op_sel_hi:[1,0]
	v_pk_mul_f32 v[14:15], v[14:15], v[36:37] op_sel_hi:[1,0]
	v_pk_mul_f32 v[16:17], v[4:5], v[16:17]
	v_pk_mul_f32 v[18:19], v[42:43], v[18:19]
	v_pk_mul_f32 v[14:15], v[2:3], v[14:15]
	v_pk_mul_f32 v[16:17], v[18:19], v[16:17]
	v_pk_mul_f32 v[14:15], v[38:39], v[14:15]
	s_nop 0
	v_cvt_pk_bf16_f32 v14, v14, v15
	v_cvt_pk_bf16_f32 v15, v16, v17
	v_lshl_add_u64 v[16:17], s[56:57], 0, v[8:9]
	v_add_co_u32_e32 v18, vcc, s5, v16
	v_lshl_add_u64 v[8:9], v[8:9], 0, s[8:9]
	s_nop 0
	v_addc_co_u32_e32 v19, vcc, 0, v17, vcc
	v_add_co_u32_e32 v12, vcc, s0, v12
	flat_store_dwordx2 v[18:19], v[14:15] offset:2048
	s_nop 0
	v_addc_co_u32_e32 v13, vcc, 0, v13, vcc
	flat_load_dwordx2 v[12:13], v[12:13] offset:3072
	v_add_u32_e32 v14, 0x404, v35
	v_add_u32_e32 v18, 0x40c, v35
	ds_read2_b32 v[14:15], v14 offset1:1
	ds_read2_b32 v[18:19], v18 offset1:1
	s_waitcnt lgkmcnt(0)
	v_mov_b32_e32 v38, v15
	v_mov_b32_e32 v39, v19
	v_mov_b32_e32 v36, v14
	v_mov_b32_e32 v37, v18
	v_pk_mul_f32 v[38:39], v[38:39], v[38:39]
	s_nop 0
	v_pk_fma_f32 v[36:37], v[36:37], v[36:37], v[38:39]
	s_nop 0
	v_add_f32_e32 v35, v36, v37
	s_nop 1
	v_add_f32_dpp v35, v35, v35 quad_perm:[1,0,3,2] row_mask:0xf bank_mask:0xf
	s_nop 1
	v_add_f32_dpp v35, v35, v35 quad_perm:[2,3,0,1] row_mask:0xf bank_mask:0xf
	s_nop 1
	v_add_f32_dpp v35, v35, v35 row_half_mirror row_mask:0xf bank_mask:0xf
	s_nop 1
	v_add_f32_dpp v35, v35, v35 row_mirror row_mask:0xf bank_mask:0xf
	s_nop 1
	v_add_f32_dpp v35, v35, v35 row_bcast:15 row_mask:0xa bank_mask:0xf
	s_nop 1
	v_add_f32_dpp v35, v35, v35 row_bcast:31 row_mask:0xc bank_mask:0xf
	s_nop 1
	v_readlane_b32 vcc_lo, v35, 63
	s_waitcnt lgkmcnt(0)
	s_nop 1
	v_mov_b32_e32 v35, vcc_lo
	v_fmamk_f32 v35, v35, 0x3b800000, v218
	v_cmp_gt_f32_e32 vcc, s30, v35
	v_mul_f32_e32 v36, 0x4f800000, v35
	s_nop 0
	v_cndmask_b32_e32 v35, v35, v36, vcc
	v_sqrt_f32_e32 v36, v35
	s_nop 0
	v_add_u32_e32 v37, -1, v36
	v_fma_f32 v38, -v37, v36, v35
	v_cmp_ge_f32_e64 s[0:1], 0, v38
	v_add_u32_e32 v38, 1, v36
	s_nop 0
	v_cndmask_b32_e64 v37, v36, v37, s[0:1]
	v_fma_f32 v36, -v38, v36, v35
	v_cmp_lt_f32_e64 s[0:1], 0, v36
	s_nop 1
	v_cndmask_b32_e64 v36, v37, v38, s[0:1]
	v_mul_f32_e32 v37, 0x37800000, v36
	v_cndmask_b32_e32 v36, v36, v37, vcc
	v_cmp_class_f32_e32 vcc, v35, v219
	s_nop 1
	v_cndmask_b32_e32 v35, v36, v35, vcc
	v_div_scale_f32 v36, s[0:1], v35, v35, 1.0
	v_rcp_f32_e32 v37, v36
	s_mov_b64 s[0:1], 0x3400
	v_lshl_add_u64 v[10:11], v[10:11], 0, s[0:1]
	v_fma_f32 v38, -v36, v37, 1.0
	v_fmac_f32_e32 v37, v38, v37
	v_div_scale_f32 v38, vcc, 1.0, v35, 1.0
	v_mul_f32_e32 v39, v38, v37
	v_fma_f32 v40, -v36, v39, v38
	v_fmac_f32_e32 v39, v40, v37
	v_fma_f32 v36, -v36, v39, v38
	s_waitcnt vmcnt(0)
	v_lshlrev_b32_e32 v38, 16, v12
	v_div_fmas_f32 v36, v36, v37, v39
	v_and_b32_e32 v39, 0xffff0000, v12
	v_mul_f32_e32 v12, 0xbfb8aa3b, v38
	v_exp_f32_e32 v12, v12
	v_div_fixup_f32 v36, v36, v35, 1.0
	v_pk_mul_f32 v[18:19], v[18:19], v[36:37] op_sel_hi:[1,0]
	v_pk_mul_f32 v[14:15], v[14:15], v[36:37] op_sel_hi:[1,0]
	v_add_f32_e32 v12, 1.0, v12
	v_rcp_f32_e32 v40, v12
	v_mul_f32_e32 v12, 0xbfb8aa3b, v39
	v_exp_f32_e32 v12, v12
	v_pk_mul_f32 v[14:15], v[2:3], v[14:15]
	v_pk_mul_f32 v[18:19], v[4:5], v[18:19]
	v_add_f32_e32 v12, 1.0, v12
	v_rcp_f32_e32 v41, v12
	v_lshlrev_b32_e32 v12, 16, v13
	v_mul_f32_e32 v35, 0xbfb8aa3b, v12
	v_exp_f32_e32 v35, v35
	v_and_b32_e32 v13, 0xffff0000, v13
	v_pk_mul_f32 v[38:39], v[40:41], v[38:39]
	v_add_f32_e32 v35, 1.0, v35
	v_rcp_f32_e32 v42, v35
	v_mul_f32_e32 v35, 0xbfb8aa3b, v13
	v_exp_f32_e32 v35, v35
	v_pk_mul_f32 v[14:15], v[38:39], v[14:15]
	v_add_f32_e32 v35, 1.0, v35
	v_rcp_f32_e32 v43, v35
	v_cvt_pk_bf16_f32 v14, v14, v15
	v_pk_mul_f32 v[12:13], v[42:43], v[12:13]
	s_nop 0
	v_pk_mul_f32 v[12:13], v[12:13], v[18:19]
	s_nop 0
	v_cvt_pk_bf16_f32 v15, v12, v13
	v_add_co_u32_e32 v12, vcc, 0x29101000, v16
	s_nop 1
	v_addc_co_u32_e32 v13, vcc, 0, v17, vcc
	flat_store_dwordx2 v[12:13], v[14:15] offset:2048
	s_cbranch_scc0 .LBB0_471
	s_add_i32 s39, s39, s67
	s_add_i32 s38, s38, s3
	s_add_i32 s11, s11, s10
	s_cmpk_gt_i32 s39, 0x3ff
	s_cbranch_scc0 .LBB0_470
